# seams: early L2 write-back started by the fourth-to-last arriver on the XCD (vAdd 3)
# baseline (speedup 1.0000x reference)
; __device__ __forceinline__ unsigned xb_ld(unsigned* p)              { return __hip_atomic_load(p, __ATOMIC_RELAXED, __HIP_MEMORY_SCOPE_AGENT); }
; __device__ __forceinline__ unsigned xb_add(unsigned* p, unsigned v) { return __hip_atomic_fetch_add(p, v, __ATOMIC_RELAXED, __HIP_MEMORY_SCOPE_AGENT); }
; #define XB_SPIN(cond, bar) do { unsigned _sp = 0; while (cond) { __builtin_amdgcn_s_sleep(1); \
;     if ((++_sp & 255u) == 0u) { if (xb_ld(&(bar)[XB_TMO])) break; if (_sp > XB_SPIN_CAP) { atomicAdd(&(bar)[XB_TMO], 1u); break; } } } } while (0)
; __device__ __forceinline__ void xcd_barrier(const XcdBarrier& b, const int wv) {
;     ...
;         unsigned nloc = b.st[0], nx = b.st[1];
;         if (nloc == 0u) { xcd_barrier_complete(bar, b.x, nloc, nx); b.st[0] = nloc; b.st[1] = nx; }
;         const unsigned old = xb_add(&bar[XB_XSUB(b.x)], 1u);
;         const unsigned gen = old / nloc;
;         if (old + 1u == (gen + 1u) * nloc) {
;             __builtin_amdgcn_fence(__ATOMIC_RELEASE, "agent");
;             asm volatile("s_waitcnt vmcnt(0)" ::: "memory");
;             const unsigned og = xb_add(&bar[XB_TOP], 1u);
;             const unsigned tg = og / nx;
;             if (og + 1u == (tg + 1u) * nx) xb_add(&bar[XB_TOPGEN], 1u);
;             else XB_SPIN(xb_ld(&bar[XB_TOPGEN]) == tg, bar);
.Lseam1_328:
	s_or_b64 exec, exec, s[14:15]
	v_cvt_f32_u32_e32 v4, v2
	s_waitcnt vmcnt(0)
	v_readfirstlane_b32 s3, v3
	v_sub_u32_e32 v3, 0, v2
	v_rcp_iflag_f32_e32 v4, v4
	v_add_u32_e32 v5, s3, v1
	v_mul_f32_e32 v4, 0x4f7ffffe, v4
	v_cvt_u32_f32_e32 v4, v4
	v_mul_lo_u32 v1, v3, v4
	v_mul_hi_u32 v1, v4, v1
	v_add_u32_e32 v1, v4, v1
	v_mul_hi_u32 v1, v5, v1
	v_mul_lo_u32 v3, v1, v2
	v_sub_u32_e32 v3, v5, v3
	v_add_u32_e32 v4, 1, v1
	v_cmp_ge_u32_e32 vcc, v3, v2
	s_nop 1
	v_cndmask_b32_e32 v1, v1, v4, vcc
	v_sub_u32_e32 v4, v3, v2
	v_cndmask_b32_e32 v3, v3, v4, vcc
	v_add_u32_e32 v4, 1, v1
	v_cmp_ge_u32_e32 vcc, v3, v2
	v_add_u32_e32 v3, 1, v5
	s_nop 0
	v_cndmask_b32_e32 v1, v1, v4, vcc
	v_mul_lo_u32 v4, v2, v1
	v_add_u32_e32 v2, v4, v2
	v_cmp_ne_u32_e32 vcc, v3, v2
	s_and_saveexec_b64 s[12:13], vcc
	s_xor_b64 s[12:13], exec, s[12:13]
	s_cbranch_execz .Lseam1_342
	v_add_u32_e32 v19, 3, v3
	v_cmp_eq_u32_e32 vcc, v19, v2
	s_cbranch_vccz .Lpf2_0
	buffer_wbl2 sc1

; __device__ __forceinline__ unsigned xb_ld(unsigned* p)              { return __hip_atomic_load(p, __ATOMIC_RELAXED, __HIP_MEMORY_SCOPE_AGENT); }
; __device__ __forceinline__ unsigned xb_add(unsigned* p, unsigned v) { return __hip_atomic_fetch_add(p, v, __ATOMIC_RELAXED, __HIP_MEMORY_SCOPE_AGENT); }
; #define XB_SPIN(cond, bar) do { unsigned _sp = 0; while (cond) { __builtin_amdgcn_s_sleep(1); \
;     if ((++_sp & 255u) == 0u) { if (xb_ld(&(bar)[XB_TMO])) break; if (_sp > XB_SPIN_CAP) { atomicAdd(&(bar)[XB_TMO], 1u); break; } } } } while (0)
; __device__ __forceinline__ void xcd_barrier(const XcdBarrier& b, const int wv) {
;     ...
;         unsigned nloc = b.st[0], nx = b.st[1];
;         if (nloc == 0u) { xcd_barrier_complete(bar, b.x, nloc, nx); b.st[0] = nloc; b.st[1] = nx; }
;         const unsigned old = xb_add(&bar[XB_XSUB(b.x)], 1u);
;         const unsigned gen = old / nloc;
;         if (old + 1u == (gen + 1u) * nloc) {
;             __builtin_amdgcn_fence(__ATOMIC_RELEASE, "agent");
;             asm volatile("s_waitcnt vmcnt(0)" ::: "memory");
;             const unsigned og = xb_add(&bar[XB_TOP], 1u);
;             const unsigned tg = og / nx;
;             if (og + 1u == (tg + 1u) * nx) xb_add(&bar[XB_TOPGEN], 1u);
;             else XB_SPIN(xb_ld(&bar[XB_TOPGEN]) == tg, bar);
.LBB0_727:
	s_or_b64 exec, exec, s[16:17]
	v_cvt_f32_u32_e32 v4, v2
	s_waitcnt vmcnt(0)
	v_readfirstlane_b32 s3, v3
	v_sub_u32_e32 v3, 0, v2
	v_rcp_iflag_f32_e32 v4, v4
	v_add_u32_e32 v5, s3, v1
	v_mul_f32_e32 v4, 0x4f7ffffe, v4
	v_cvt_u32_f32_e32 v4, v4
	v_mul_lo_u32 v1, v3, v4
	v_mul_hi_u32 v1, v4, v1
	v_add_u32_e32 v1, v4, v1
	v_mul_hi_u32 v1, v5, v1
	v_mul_lo_u32 v3, v1, v2
	v_sub_u32_e32 v3, v5, v3
	v_add_u32_e32 v4, 1, v1
	v_cmp_ge_u32_e32 vcc, v3, v2
	s_nop 1
	v_cndmask_b32_e32 v1, v1, v4, vcc
	v_sub_u32_e32 v4, v3, v2
	v_cndmask_b32_e32 v3, v3, v4, vcc
	v_add_u32_e32 v4, 1, v1
	v_cmp_ge_u32_e32 vcc, v3, v2
	v_add_u32_e32 v3, 1, v5
	s_nop 0
	v_cndmask_b32_e32 v1, v1, v4, vcc
	v_mul_lo_u32 v4, v2, v1
	v_add_u32_e32 v2, v4, v2
	v_cmp_ne_u32_e32 vcc, v3, v2
	s_and_saveexec_b64 s[14:15], vcc
	s_xor_b64 s[14:15], exec, s[14:15]
	s_cbranch_execz .LBB0_741
	v_add_u32_e32 v19, 3, v3
	v_cmp_eq_u32_e32 vcc, v19, v2
	s_cbranch_vccz .Lpf2_4
	buffer_wbl2 sc1

; __device__ __forceinline__ unsigned xb_ld(unsigned* p)              { return __hip_atomic_load(p, __ATOMIC_RELAXED, __HIP_MEMORY_SCOPE_AGENT); }
; __device__ __forceinline__ unsigned xb_add(unsigned* p, unsigned v) { return __hip_atomic_fetch_add(p, v, __ATOMIC_RELAXED, __HIP_MEMORY_SCOPE_AGENT); }
; #define XB_SPIN(cond, bar) do { unsigned _sp = 0; while (cond) { __builtin_amdgcn_s_sleep(1); \
;     if ((++_sp & 255u) == 0u) { if (xb_ld(&(bar)[XB_TMO])) break; if (_sp > XB_SPIN_CAP) { atomicAdd(&(bar)[XB_TMO], 1u); break; } } } } while (0)
; __device__ __forceinline__ void xcd_barrier(const XcdBarrier& b, const int wv) {
;     ...
;         unsigned nloc = b.st[0], nx = b.st[1];
;         if (nloc == 0u) { xcd_barrier_complete(bar, b.x, nloc, nx); b.st[0] = nloc; b.st[1] = nx; }
;         const unsigned old = xb_add(&bar[XB_XSUB(b.x)], 1u);
;         const unsigned gen = old / nloc;
;         if (old + 1u == (gen + 1u) * nloc) {
;             __builtin_amdgcn_fence(__ATOMIC_RELEASE, "agent");
;             asm volatile("s_waitcnt vmcnt(0)" ::: "memory");
;             const unsigned og = xb_add(&bar[XB_TOP], 1u);
;             const unsigned tg = og / nx;
;             if (og + 1u == (tg + 1u) * nx) xb_add(&bar[XB_TOPGEN], 1u);
;             else XB_SPIN(xb_ld(&bar[XB_TOPGEN]) == tg, bar);
.LBB0_860:
	s_or_b64 exec, exec, s[18:19]
	v_cvt_f32_u32_e32 v4, v2
	s_waitcnt vmcnt(0)
	v_readfirstlane_b32 s3, v3
	v_sub_u32_e32 v3, 0, v2
	v_rcp_iflag_f32_e32 v4, v4
	v_add_u32_e32 v5, s3, v1
	v_mul_f32_e32 v4, 0x4f7ffffe, v4
	v_cvt_u32_f32_e32 v4, v4
	v_mul_lo_u32 v1, v3, v4
	v_mul_hi_u32 v1, v4, v1
	v_add_u32_e32 v1, v4, v1
	v_mul_hi_u32 v1, v5, v1
	v_mul_lo_u32 v3, v1, v2
	v_sub_u32_e32 v3, v5, v3
	v_add_u32_e32 v4, 1, v1
	v_cmp_ge_u32_e32 vcc, v3, v2
	s_nop 1
	v_cndmask_b32_e32 v1, v1, v4, vcc
	v_sub_u32_e32 v4, v3, v2
	v_cndmask_b32_e32 v3, v3, v4, vcc
	v_add_u32_e32 v4, 1, v1
	v_cmp_ge_u32_e32 vcc, v3, v2
	v_add_u32_e32 v3, 1, v5
	s_nop 0
	v_cndmask_b32_e32 v1, v1, v4, vcc
	v_mul_lo_u32 v4, v2, v1
	v_add_u32_e32 v2, v4, v2
	v_cmp_ne_u32_e32 vcc, v3, v2
	s_and_saveexec_b64 s[16:17], vcc
	s_xor_b64 s[16:17], exec, s[16:17]
	s_cbranch_execz .LBB0_874
	v_add_u32_e32 v19, 3, v3
	v_cmp_eq_u32_e32 vcc, v19, v2
	s_cbranch_vccz .Lpf2_6
	buffer_wbl2 sc1
